# EpiSwiglu: hoist 8 SS row-scale loads to epilogue top, drop per-iteration vmcnt(0)
# speedup vs baseline: 1.0110x; 1.0110x over previous
; __device__ __forceinline__ unsigned cvt_pk_bf16(float lo, float hi) { unsigned r; asm volatile("v_cvt_pk_bf16_f32 %0, %1, %2" : "=v"(r) : "v"(lo), "v"(hi)); return r; }
;     __device__ __forceinline__ static float sg(float g, float u) { return g * u * __builtin_amdgcn_rcpf(1.0f + __builtin_amdgcn_exp2f(-1.4426950408889634f * g)); }
;     __device__ __forceinline__ void operator()(const f32x4 (&acc)[2][2][4][2], const Unit& u, int wr, int wc, int fr, int fq) const {
;         const int row0 = u.pm * BM + wr * 64 + fr, col0 = u.pn * BM + wc * 32 + 8 * fq, j0 = u.pn * HALF + wc * 32 + 8 * fq;
;         const float* bp = bt + (size_t)((u.pm * BM) >> 12) * (2 * 2816) + col0;
;         f32x4 bv[2][2];
; #pragma unroll
;         for (int bj = 0; bj < 2; ++bj)
; #pragma unroll
;             for (int n = 0; n < 2; ++n) bv[bj][n] = *(const f32x4*)(bp + bj * HALF + 4 * n);
; #pragma unroll
;         for (int ai = 0; ai < 2; ++ai)
; #pragma unroll
;             for (int m = 0; m < 4; ++m) { const int row = row0 + ai * HALF + m * 16;
;                 const float rstd = __builtin_amdgcn_rsqf(SS[row] * (1.0f / 1024.0f) + 1e-6f);
;                 const f32x4 g0 = acc[ai][0][m][0] * rstd + bv[0][0], g1 = acc[ai][0][m][1] * rstd + bv[0][1], u0 = acc[ai][1][m][0] * rstd + bv[1][0], u1 = acc[ai][1][m][1] * rstd + bv[1][1];
;                 u32x4 w; w.x = cvt_pk_bf16(sg(g0[0], u0[0]), sg(g0[1], u0[1])); w.y = cvt_pk_bf16(sg(g0[2], u0[2]), sg(g0[3], u0[3]));
;                 w.z = cvt_pk_bf16(sg(g1[0], u1[0]), sg(g1[1], u1[1])); w.w = cvt_pk_bf16(sg(g1[2], u1[2]), sg(g1[3], u1[3]));
;                 *(u32x4*)(O + (size_t)row * ldc + j0) = w; }
.LBB0_804:
	s_lshl_b32 s0, s70, 8
	v_mov_b32_e32 v129, v204
	s_add_i32 s0, s0, s60
	s_lshl_b32 s1, s71, 8
	v_lshrrev_b32_e32 v128, 1, v129
	v_and_or_b32 v160, v129, 15, s0
	s_or_b32 s1, s1, s16
	v_and_b32_e32 v166, 24, v128
	v_ashrrev_i32_e32 v161, 31, v160
	v_or_b32_e32 v128, s1, v166
	s_lshl_b32 s1, s71, 7
	v_lshl_add_u64 v[162:163], v[160:161], 2, s[10:11]
	s_or_b32 s22, s1, s16
	s_ashr_i32 s1, s70, 4
	global_load_dword v161, v[162:163], off
	global_load_dword v182, v[162:163], off offset:64
	global_load_dword v183, v[162:163], off offset:128
	global_load_dword v184, v[162:163], off offset:192
	global_load_dword v185, v[162:163], off offset:512
	global_load_dword v186, v[162:163], off offset:576
	global_load_dword v187, v[162:163], off offset:640
	global_load_dword v188, v[162:163], off offset:704
	s_mul_hi_i32 s23, s1, 0x5800
	s_mulk_i32 s1, 0x5800
	s_add_u32 s0, s17, s1
	s_addc_u32 s1, s36, s23
	v_ashrrev_i32_e32 v129, 31, v128
	v_lshl_add_u64 v[128:129], v[128:129], 2, s[0:1]
	global_load_dwordx4 v[140:143], v[128:129], off
	global_load_dwordx4 v[136:139], v[128:129], off offset:16
	global_load_dwordx4 v[132:135], v[128:129], off offset:512
	s_nop 0
	global_load_dwordx4 v[128:131], v[128:129], off offset:528
	v_or_b32_e32 v166, s22, v166
	v_mov_b64_e32 v[164:165], s[20:21]
	v_ashrrev_i32_e32 v167, 31, v166
	v_mad_i64_i32 v[174:175], s[0:1], v160, s67, v[164:165]
	v_or_b32_e32 v176, 16, v160
	v_lshlrev_b64 v[166:167], 1, v[166:167]
	v_ashrrev_i32_e32 v177, 31, v176
	v_lshl_add_u64 v[174:175], v[174:175], 0, v[166:167]
	v_lshl_add_u64 v[180:181], v[176:177], 2, s[10:11]
	s_and_b64 vcc, exec, s[6:7]
	s_mov_b64 s[6:7], -1
	s_waitcnt vmcnt(0)
	v_fmamk_f32 v161, v161, 0x3a800000, v172
	v_rsq_f32_e32 v178, v161
	s_nop 0
	v_pk_fma_f32 v[126:127], v[126:127], v[178:179], v[138:139] op_sel_hi:[1,0,1]
	v_pk_fma_f32 v[122:123], v[122:123], v[178:179], v[142:143] op_sel_hi:[1,0,1]
	v_pk_fma_f32 v[114:115], v[114:115], v[178:179], v[130:131] op_sel_hi:[1,0,1]
	v_pk_fma_f32 v[120:121], v[120:121], v[178:179], v[140:141] op_sel_hi:[1,0,1]
	v_pk_fma_f32 v[124:125], v[124:125], v[178:179], v[136:137] op_sel_hi:[1,0,1]
	v_pk_fma_f32 v[118:119], v[118:119], v[178:179], v[134:135] op_sel_hi:[1,0,1]
	v_pk_fma_f32 v[116:117], v[116:117], v[178:179], v[132:133] op_sel_hi:[1,0,1]
	v_pk_fma_f32 v[112:113], v[112:113], v[178:179], v[128:129] op_sel_hi:[1,0,1]
	v_mul_f32_e32 v115, v127, v115
	v_mul_f32_e32 v127, 0xbfb8aa3b, v127
	v_mul_f32_e32 v116, v120, v116
	v_mul_f32_e32 v120, 0xbfb8aa3b, v120
	v_mul_f32_e32 v117, v121, v117
	v_mul_f32_e32 v121, 0xbfb8aa3b, v121
	v_mul_f32_e32 v118, v122, v118
	v_mul_f32_e32 v122, 0xbfb8aa3b, v122
	v_mul_f32_e32 v119, v123, v119
	v_mul_f32_e32 v123, 0xbfb8aa3b, v123
	v_mul_f32_e32 v112, v124, v112
	v_mul_f32_e32 v124, 0xbfb8aa3b, v124
	v_mul_f32_e32 v113, v125, v113
	v_mul_f32_e32 v125, 0xbfb8aa3b, v125
	v_mul_f32_e32 v114, v126, v114
	v_mul_f32_e32 v126, 0xbfb8aa3b, v126
	v_exp_f32_e32 v127, v127
	v_exp_f32_e32 v120, v120
	v_exp_f32_e32 v121, v121
	v_exp_f32_e32 v122, v122
	v_exp_f32_e32 v123, v123
	v_exp_f32_e32 v124, v124
	v_exp_f32_e32 v125, v125
	v_exp_f32_e32 v126, v126
	v_add_f32_e32 v127, 1.0, v127
	v_add_f32_e32 v120, 1.0, v120
	v_add_f32_e32 v121, 1.0, v121
	v_add_f32_e32 v122, 1.0, v122
	v_add_f32_e32 v123, 1.0, v123
	v_add_f32_e32 v124, 1.0, v124
	v_add_f32_e32 v125, 1.0, v125
	v_add_f32_e32 v126, 1.0, v126
	v_rcp_f32_e32 v127, v127
	v_rcp_f32_e32 v120, v120
	v_rcp_f32_e32 v121, v121
	v_rcp_f32_e32 v122, v122
	v_rcp_f32_e32 v123, v123
	v_rcp_f32_e32 v124, v124
	v_rcp_f32_e32 v125, v125
	v_rcp_f32_e32 v126, v126
	v_mul_f32_e32 v115, v115, v127
	v_mul_f32_e32 v116, v116, v120
	v_mul_f32_e32 v117, v117, v121
	v_mul_f32_e32 v118, v118, v122
	v_mul_f32_e32 v119, v119, v123
	v_mul_f32_e32 v120, v112, v124
	v_mul_f32_e32 v121, v113, v125
	v_mul_f32_e32 v122, v114, v126
	v_cvt_pk_bf16_f32 v112, v116, v117
	v_cvt_pk_bf16_f32 v113, v118, v119
	v_cvt_pk_bf16_f32 v114, v120, v121
	v_cvt_pk_bf16_f32 v115, v122, v115
	global_store_dwordx4 v[174:175], v[112:115], off
	s_nop 0
	s_nop 0
	v_or_b32_e32 v112, 32, v160
	v_mad_i64_i32 v[114:115], s[0:1], v176, s67, v[164:165]
	v_lshl_add_u64 v[114:115], v[114:115], 0, v[166:167]
	v_fmamk_f32 v113, v182, 0x3a800000, v172
	v_rsq_f32_e32 v116, v113
	v_ashrrev_i32_e32 v113, 31, v112
	v_lshl_add_u64 v[118:119], v[112:113], 2, s[10:11]
	v_pk_fma_f32 v[106:107], v[106:107], v[116:117], v[138:139] op_sel_hi:[1,0,1]
	v_pk_fma_f32 v[98:99], v[98:99], v[116:117], v[130:131] op_sel_hi:[1,0,1]
	v_pk_fma_f32 v[110:111], v[110:111], v[116:117], v[142:143] op_sel_hi:[1,0,1]
	v_pk_fma_f32 v[108:109], v[108:109], v[116:117], v[140:141] op_sel_hi:[1,0,1]
	v_pk_fma_f32 v[104:105], v[104:105], v[116:117], v[136:137] op_sel_hi:[1,0,1]
	v_pk_fma_f32 v[102:103], v[102:103], v[116:117], v[134:135] op_sel_hi:[1,0,1]
	v_pk_fma_f32 v[100:101], v[100:101], v[116:117], v[132:133] op_sel_hi:[1,0,1]
	v_pk_fma_f32 v[96:97], v[96:97], v[116:117], v[128:129] op_sel_hi:[1,0,1]
	v_mul_f32_e32 v99, v107, v99
	v_mul_f32_e32 v107, 0xbfb8aa3b, v107
	v_mul_f32_e32 v100, v108, v100
	v_mul_f32_e32 v108, 0xbfb8aa3b, v108
	v_mul_f32_e32 v101, v109, v101
	v_mul_f32_e32 v109, 0xbfb8aa3b, v109
	v_mul_f32_e32 v102, v110, v102
	v_mul_f32_e32 v110, 0xbfb8aa3b, v110
	v_mul_f32_e32 v103, v111, v103
	v_mul_f32_e32 v111, 0xbfb8aa3b, v111
	v_mul_f32_e32 v96, v104, v96
	v_mul_f32_e32 v104, 0xbfb8aa3b, v104
	v_mul_f32_e32 v97, v105, v97
	v_mul_f32_e32 v105, 0xbfb8aa3b, v105
	v_mul_f32_e32 v98, v106, v98
	v_mul_f32_e32 v106, 0xbfb8aa3b, v106
	v_exp_f32_e32 v107, v107
	v_exp_f32_e32 v108, v108
	v_exp_f32_e32 v109, v109
	v_exp_f32_e32 v110, v110
; __device__ __forceinline__ unsigned cvt_pk_bf16(float lo, float hi) { unsigned r; asm volatile("v_cvt_pk_bf16_f32 %0, %1, %2" : "=v"(r) : "v"(lo), "v"(hi)); return r; }
;     __device__ __forceinline__ static float sg(float g, float u) { return g * u * __builtin_amdgcn_rcpf(1.0f + __builtin_amdgcn_exp2f(-1.4426950408889634f * g)); }
;     __device__ __forceinline__ void operator()(const f32x4 (&acc)[2][2][4][2], const Unit& u, int wr, int wc, int fr, int fq) const {
;     ...
;             for (int m = 0; m < 4; ++m) { const int row = row0 + ai * HALF + m * 16;
;                 const float rstd = __builtin_amdgcn_rsqf(SS[row] * (1.0f / 1024.0f) + 1e-6f);
;                 const f32x4 g0 = acc[ai][0][m][0] * rstd + bv[0][0], g1 = acc[ai][0][m][1] * rstd + bv[0][1], u0 = acc[ai][1][m][0] * rstd + bv[1][0], u1 = acc[ai][1][m][1] * rstd + bv[1][1];
;                 u32x4 w; w.x = cvt_pk_bf16(sg(g0[0], u0[0]), sg(g0[1], u0[1])); w.y = cvt_pk_bf16(sg(g0[2], u0[2]), sg(g0[3], u0[3]));
;                 w.z = cvt_pk_bf16(sg(g1[0], u1[0]), sg(g1[1], u1[1])); w.w = cvt_pk_bf16(sg(g1[2], u1[2]), sg(g1[3], u1[3]));
;                 *(u32x4*)(O + (size_t)row * ldc + j0) = w; }
	v_exp_f32_e32 v111, v111
	v_exp_f32_e32 v104, v104
	v_exp_f32_e32 v105, v105
	v_exp_f32_e32 v106, v106
	v_add_f32_e32 v107, 1.0, v107
	v_add_f32_e32 v108, 1.0, v108
	v_add_f32_e32 v109, 1.0, v109
	v_add_f32_e32 v110, 1.0, v110
	v_add_f32_e32 v111, 1.0, v111
	v_add_f32_e32 v104, 1.0, v104
	v_add_f32_e32 v105, 1.0, v105
	v_add_f32_e32 v106, 1.0, v106
	v_rcp_f32_e32 v107, v107
	v_rcp_f32_e32 v108, v108
	v_rcp_f32_e32 v109, v109
	v_rcp_f32_e32 v110, v110
	v_rcp_f32_e32 v111, v111
	v_rcp_f32_e32 v104, v104
	v_rcp_f32_e32 v105, v105
	v_rcp_f32_e32 v106, v106
	v_mul_f32_e32 v99, v99, v107
	v_mul_f32_e32 v100, v100, v108
	v_mul_f32_e32 v101, v101, v109
	v_mul_f32_e32 v102, v102, v110
	v_mul_f32_e32 v103, v103, v111
	v_mul_f32_e32 v104, v96, v104
	v_mul_f32_e32 v105, v97, v105
	v_mul_f32_e32 v106, v98, v106
	v_cvt_pk_bf16_f32 v96, v100, v101
	v_cvt_pk_bf16_f32 v97, v102, v103
	v_cvt_pk_bf16_f32 v98, v104, v105
	v_cvt_pk_bf16_f32 v99, v106, v99
	global_store_dwordx4 v[114:115], v[96:99], off
	s_nop 0
	s_nop 0
	v_or_b32_e32 v96, 48, v160
	v_mad_i64_i32 v[98:99], s[0:1], v112, s67, v[164:165]
	v_lshl_add_u64 v[98:99], v[98:99], 0, v[166:167]
	v_fmamk_f32 v97, v183, 0x3a800000, v172
	v_rsq_f32_e32 v100, v97
	v_ashrrev_i32_e32 v97, 31, v96
	v_lshl_add_u64 v[102:103], v[96:97], 2, s[10:11]
	v_pk_fma_f32 v[90:91], v[90:91], v[100:101], v[138:139] op_sel_hi:[1,0,1]
	v_pk_fma_f32 v[82:83], v[82:83], v[100:101], v[130:131] op_sel_hi:[1,0,1]
	v_pk_fma_f32 v[94:95], v[94:95], v[100:101], v[142:143] op_sel_hi:[1,0,1]
	v_pk_fma_f32 v[92:93], v[92:93], v[100:101], v[140:141] op_sel_hi:[1,0,1]
	v_pk_fma_f32 v[88:89], v[88:89], v[100:101], v[136:137] op_sel_hi:[1,0,1]
	v_pk_fma_f32 v[86:87], v[86:87], v[100:101], v[134:135] op_sel_hi:[1,0,1]
	v_pk_fma_f32 v[84:85], v[84:85], v[100:101], v[132:133] op_sel_hi:[1,0,1]
	v_pk_fma_f32 v[80:81], v[80:81], v[100:101], v[128:129] op_sel_hi:[1,0,1]
	v_mul_f32_e32 v83, v91, v83
	v_mul_f32_e32 v91, 0xbfb8aa3b, v91
	v_mul_f32_e32 v84, v92, v84
	v_mul_f32_e32 v92, 0xbfb8aa3b, v92
	v_mul_f32_e32 v85, v93, v85
	v_mul_f32_e32 v93, 0xbfb8aa3b, v93
	v_mul_f32_e32 v86, v94, v86
	v_mul_f32_e32 v94, 0xbfb8aa3b, v94
	v_mul_f32_e32 v87, v95, v87
	v_mul_f32_e32 v95, 0xbfb8aa3b, v95
	v_mul_f32_e32 v80, v88, v80
	v_mul_f32_e32 v88, 0xbfb8aa3b, v88
	v_mul_f32_e32 v81, v89, v81
	v_mul_f32_e32 v89, 0xbfb8aa3b, v89
	v_mul_f32_e32 v82, v90, v82
	v_mul_f32_e32 v90, 0xbfb8aa3b, v90
	v_exp_f32_e32 v91, v91
	v_exp_f32_e32 v92, v92
	v_exp_f32_e32 v93, v93
	v_exp_f32_e32 v94, v94
	v_exp_f32_e32 v95, v95
	v_exp_f32_e32 v88, v88
	v_exp_f32_e32 v89, v89
	v_exp_f32_e32 v90, v90
	v_add_f32_e32 v91, 1.0, v91
	v_add_f32_e32 v92, 1.0, v92
	v_add_f32_e32 v93, 1.0, v93
	v_add_f32_e32 v94, 1.0, v94
	v_add_f32_e32 v95, 1.0, v95
	v_add_f32_e32 v88, 1.0, v88
	v_add_f32_e32 v89, 1.0, v89
	v_add_f32_e32 v90, 1.0, v90
	v_rcp_f32_e32 v91, v91
	v_rcp_f32_e32 v92, v92
	v_rcp_f32_e32 v93, v93
	v_rcp_f32_e32 v94, v94
	v_rcp_f32_e32 v95, v95
	v_rcp_f32_e32 v88, v88
	v_rcp_f32_e32 v89, v89
	v_rcp_f32_e32 v90, v90
	v_mul_f32_e32 v83, v83, v91
	v_mul_f32_e32 v84, v84, v92
	v_mul_f32_e32 v85, v85, v93
	v_mul_f32_e32 v86, v86, v94
	v_mul_f32_e32 v87, v87, v95
	v_mul_f32_e32 v88, v80, v88
	v_mul_f32_e32 v89, v81, v89
	v_mul_f32_e32 v90, v82, v90
	v_cvt_pk_bf16_f32 v80, v84, v85
	v_cvt_pk_bf16_f32 v81, v86, v87
	v_cvt_pk_bf16_f32 v82, v88, v89
	v_cvt_pk_bf16_f32 v83, v90, v83
	global_store_dwordx4 v[98:99], v[80:83], off
	s_nop 0
	s_nop 0
	v_mad_i64_i32 v[82:83], s[0:1], v96, s67, v[164:165]
	v_lshl_add_u64 v[82:83], v[82:83], 0, v[166:167]
	v_fmamk_f32 v80, v184, 0x3a800000, v172
	v_rsq_f32_e32 v80, v80
	s_nop 0
	v_pk_fma_f32 v[74:75], v[74:75], v[80:81], v[138:139] op_sel_hi:[1,0,1]
	v_pk_fma_f32 v[66:67], v[66:67], v[80:81], v[130:131] op_sel_hi:[1,0,1]
	v_pk_fma_f32 v[78:79], v[78:79], v[80:81], v[142:143] op_sel_hi:[1,0,1]
	v_pk_fma_f32 v[76:77], v[76:77], v[80:81], v[140:141] op_sel_hi:[1,0,1]
	v_pk_fma_f32 v[72:73], v[72:73], v[80:81], v[136:137] op_sel_hi:[1,0,1]
	v_pk_fma_f32 v[70:71], v[70:71], v[80:81], v[134:135] op_sel_hi:[1,0,1]
	v_pk_fma_f32 v[68:69], v[68:69], v[80:81], v[132:133] op_sel_hi:[1,0,1]
	v_pk_fma_f32 v[64:65], v[64:65], v[80:81], v[128:129] op_sel_hi:[1,0,1]
	v_mul_f32_e32 v67, v75, v67
	v_mul_f32_e32 v75, 0xbfb8aa3b, v75
	v_mul_f32_e32 v68, v76, v68
	v_mul_f32_e32 v76, 0xbfb8aa3b, v76
	v_mul_f32_e32 v69, v77, v69
	v_mul_f32_e32 v77, 0xbfb8aa3b, v77
	v_mul_f32_e32 v70, v78, v70
	v_mul_f32_e32 v78, 0xbfb8aa3b, v78
	v_mul_f32_e32 v71, v79, v71
	v_mul_f32_e32 v79, 0xbfb8aa3b, v79
	v_mul_f32_e32 v64, v72, v64
	v_mul_f32_e32 v72, 0xbfb8aa3b, v72
	v_mul_f32_e32 v65, v73, v65
	v_mul_f32_e32 v73, 0xbfb8aa3b, v73
	v_mul_f32_e32 v66, v74, v66
	v_mul_f32_e32 v74, 0xbfb8aa3b, v74
	v_exp_f32_e32 v75, v75
	v_exp_f32_e32 v76, v76
	v_exp_f32_e32 v77, v77
	v_exp_f32_e32 v78, v78
	v_exp_f32_e32 v79, v79
	v_exp_f32_e32 v72, v72
	v_exp_f32_e32 v73, v73
	v_exp_f32_e32 v74, v74
	v_add_f32_e32 v75, 1.0, v75
	v_add_f32_e32 v76, 1.0, v76
	v_add_f32_e32 v77, 1.0, v77
	v_add_f32_e32 v78, 1.0, v78
	v_add_f32_e32 v79, 1.0, v79
	v_add_f32_e32 v72, 1.0, v72
	v_add_f32_e32 v73, 1.0, v73
	v_add_f32_e32 v74, 1.0, v74
	v_rcp_f32_e32 v75, v75
	v_rcp_f32_e32 v76, v76
	v_rcp_f32_e32 v77, v77
	v_rcp_f32_e32 v78, v78
	v_rcp_f32_e32 v79, v79
	v_rcp_f32_e32 v72, v72
	v_rcp_f32_e32 v73, v73
	v_rcp_f32_e32 v74, v74
	v_mul_f32_e32 v67, v67, v75
	v_mul_f32_e32 v68, v68, v76
	v_mul_f32_e32 v69, v69, v77
	v_mul_f32_e32 v70, v70, v78
	v_mul_f32_e32 v71, v71, v79
	v_mul_f32_e32 v72, v64, v72
	v_mul_f32_e32 v73, v65, v73
	v_mul_f32_e32 v74, v66, v74
	v_cvt_pk_bf16_f32 v64, v68, v69
; __device__ __forceinline__ unsigned cvt_pk_bf16(float lo, float hi) { unsigned r; asm volatile("v_cvt_pk_bf16_f32 %0, %1, %2" : "=v"(r) : "v"(lo), "v"(hi)); return r; }
;     __device__ __forceinline__ static float sg(float g, float u) { return g * u * __builtin_amdgcn_rcpf(1.0f + __builtin_amdgcn_exp2f(-1.4426950408889634f * g)); }
;     __device__ __forceinline__ void operator()(const f32x4 (&acc)[2][2][4][2], const Unit& u, int wr, int wc, int fr, int fq) const {
;     ...
;             for (int m = 0; m < 4; ++m) { const int row = row0 + ai * HALF + m * 16;
;                 const float rstd = __builtin_amdgcn_rsqf(SS[row] * (1.0f / 1024.0f) + 1e-6f);
;                 const f32x4 g0 = acc[ai][0][m][0] * rstd + bv[0][0], g1 = acc[ai][0][m][1] * rstd + bv[0][1], u0 = acc[ai][1][m][0] * rstd + bv[1][0], u1 = acc[ai][1][m][1] * rstd + bv[1][1];
;                 u32x4 w; w.x = cvt_pk_bf16(sg(g0[0], u0[0]), sg(g0[1], u0[1])); w.y = cvt_pk_bf16(sg(g0[2], u0[2]), sg(g0[3], u0[3]));
;                 w.z = cvt_pk_bf16(sg(g1[0], u1[0]), sg(g1[1], u1[1])); w.w = cvt_pk_bf16(sg(g1[2], u1[2]), sg(g1[3], u1[3]));
;                 *(u32x4*)(O + (size_t)row * ldc + j0) = w; }
	v_cvt_pk_bf16_f32 v65, v70, v71
	v_cvt_pk_bf16_f32 v66, v72, v73
	v_cvt_pk_bf16_f32 v67, v74, v67
	global_store_dwordx4 v[82:83], v[64:67], off
	s_nop 0
	s_nop 0
	v_add_u32_e32 v65, 0x80, v160
	v_mad_i64_i32 v[66:67], s[0:1], v65, s67, v[164:165]
	v_lshl_add_u64 v[66:67], v[66:67], 0, v[166:167]
	v_fmamk_f32 v64, v185, 0x3a800000, v172
	v_rsq_f32_e32 v64, v64
	s_nop 0
	v_pk_fma_f32 v[58:59], v[58:59], v[64:65], v[138:139] op_sel_hi:[1,0,1]
	v_pk_fma_f32 v[50:51], v[50:51], v[64:65], v[130:131] op_sel_hi:[1,0,1]
	v_pk_fma_f32 v[62:63], v[62:63], v[64:65], v[142:143] op_sel_hi:[1,0,1]
	v_pk_fma_f32 v[60:61], v[60:61], v[64:65], v[140:141] op_sel_hi:[1,0,1]
	v_pk_fma_f32 v[56:57], v[56:57], v[64:65], v[136:137] op_sel_hi:[1,0,1]
	v_pk_fma_f32 v[54:55], v[54:55], v[64:65], v[134:135] op_sel_hi:[1,0,1]
	v_pk_fma_f32 v[52:53], v[52:53], v[64:65], v[132:133] op_sel_hi:[1,0,1]
	v_pk_fma_f32 v[48:49], v[48:49], v[64:65], v[128:129] op_sel_hi:[1,0,1]
	v_mul_f32_e32 v51, v59, v51
	v_mul_f32_e32 v59, 0xbfb8aa3b, v59
	v_mul_f32_e32 v52, v60, v52
	v_mul_f32_e32 v60, 0xbfb8aa3b, v60
	v_mul_f32_e32 v53, v61, v53
	v_mul_f32_e32 v61, 0xbfb8aa3b, v61
	v_mul_f32_e32 v54, v62, v54
	v_mul_f32_e32 v62, 0xbfb8aa3b, v62
	v_mul_f32_e32 v55, v63, v55
	v_mul_f32_e32 v63, 0xbfb8aa3b, v63
	v_mul_f32_e32 v48, v56, v48
	v_mul_f32_e32 v56, 0xbfb8aa3b, v56
	v_mul_f32_e32 v49, v57, v49
	v_mul_f32_e32 v57, 0xbfb8aa3b, v57
	v_mul_f32_e32 v50, v58, v50
	v_mul_f32_e32 v58, 0xbfb8aa3b, v58
	v_exp_f32_e32 v59, v59
	v_exp_f32_e32 v60, v60
	v_exp_f32_e32 v61, v61
	v_exp_f32_e32 v62, v62
	v_exp_f32_e32 v63, v63
	v_exp_f32_e32 v56, v56
	v_exp_f32_e32 v57, v57
	v_exp_f32_e32 v58, v58
	v_add_f32_e32 v59, 1.0, v59
	v_add_f32_e32 v60, 1.0, v60
	v_add_f32_e32 v61, 1.0, v61
	v_add_f32_e32 v62, 1.0, v62
	v_add_f32_e32 v63, 1.0, v63
	v_add_f32_e32 v56, 1.0, v56
	v_add_f32_e32 v57, 1.0, v57
	v_add_f32_e32 v58, 1.0, v58
	v_rcp_f32_e32 v59, v59
	v_rcp_f32_e32 v60, v60
	v_rcp_f32_e32 v61, v61
	v_rcp_f32_e32 v62, v62
	v_rcp_f32_e32 v63, v63
	v_rcp_f32_e32 v56, v56
	v_rcp_f32_e32 v57, v57
	v_rcp_f32_e32 v58, v58
	v_mul_f32_e32 v51, v51, v59
	v_mul_f32_e32 v52, v52, v60
	v_mul_f32_e32 v53, v53, v61
	v_mul_f32_e32 v54, v54, v62
	v_mul_f32_e32 v55, v55, v63
	v_mul_f32_e32 v56, v48, v56
	v_mul_f32_e32 v57, v49, v57
	v_mul_f32_e32 v58, v50, v58
	v_cvt_pk_bf16_f32 v48, v52, v53
	v_cvt_pk_bf16_f32 v49, v54, v55
	v_cvt_pk_bf16_f32 v50, v56, v57
	v_cvt_pk_bf16_f32 v51, v58, v51
	global_store_dwordx4 v[66:67], v[48:51], off
	s_nop 0
	s_nop 0
	v_add_u32_e32 v49, 0x90, v160
	v_mad_i64_i32 v[50:51], s[0:1], v49, s67, v[164:165]
	v_lshl_add_u64 v[50:51], v[50:51], 0, v[166:167]
	v_fmamk_f32 v48, v186, 0x3a800000, v172
	v_rsq_f32_e32 v48, v48
	s_nop 0
	v_pk_fma_f32 v[42:43], v[42:43], v[48:49], v[138:139] op_sel_hi:[1,0,1]
	v_pk_fma_f32 v[34:35], v[34:35], v[48:49], v[130:131] op_sel_hi:[1,0,1]
	v_pk_fma_f32 v[46:47], v[46:47], v[48:49], v[142:143] op_sel_hi:[1,0,1]
	v_pk_fma_f32 v[44:45], v[44:45], v[48:49], v[140:141] op_sel_hi:[1,0,1]
	v_pk_fma_f32 v[40:41], v[40:41], v[48:49], v[136:137] op_sel_hi:[1,0,1]
	v_pk_fma_f32 v[38:39], v[38:39], v[48:49], v[134:135] op_sel_hi:[1,0,1]
	v_pk_fma_f32 v[36:37], v[36:37], v[48:49], v[132:133] op_sel_hi:[1,0,1]
	v_pk_fma_f32 v[32:33], v[32:33], v[48:49], v[128:129] op_sel_hi:[1,0,1]
	v_mul_f32_e32 v35, v43, v35
	v_mul_f32_e32 v43, 0xbfb8aa3b, v43
	v_mul_f32_e32 v36, v44, v36
	v_mul_f32_e32 v44, 0xbfb8aa3b, v44
	v_mul_f32_e32 v37, v45, v37
	v_mul_f32_e32 v45, 0xbfb8aa3b, v45
	v_mul_f32_e32 v38, v46, v38
	v_mul_f32_e32 v46, 0xbfb8aa3b, v46
	v_mul_f32_e32 v39, v47, v39
	v_mul_f32_e32 v47, 0xbfb8aa3b, v47
	v_mul_f32_e32 v32, v40, v32
	v_mul_f32_e32 v40, 0xbfb8aa3b, v40
	v_mul_f32_e32 v33, v41, v33
	v_mul_f32_e32 v41, 0xbfb8aa3b, v41
	v_mul_f32_e32 v34, v42, v34
	v_mul_f32_e32 v42, 0xbfb8aa3b, v42
	v_exp_f32_e32 v43, v43
	v_exp_f32_e32 v44, v44
	v_exp_f32_e32 v45, v45
	v_exp_f32_e32 v46, v46
	v_exp_f32_e32 v47, v47
	v_exp_f32_e32 v40, v40
	v_exp_f32_e32 v41, v41
	v_exp_f32_e32 v42, v42
	v_add_f32_e32 v43, 1.0, v43
	v_add_f32_e32 v44, 1.0, v44
	v_add_f32_e32 v45, 1.0, v45
	v_add_f32_e32 v46, 1.0, v46
	v_add_f32_e32 v47, 1.0, v47
	v_add_f32_e32 v40, 1.0, v40
	v_add_f32_e32 v41, 1.0, v41
	v_add_f32_e32 v42, 1.0, v42
	v_rcp_f32_e32 v43, v43
	v_rcp_f32_e32 v44, v44
	v_rcp_f32_e32 v45, v45
	v_rcp_f32_e32 v46, v46
	v_rcp_f32_e32 v47, v47
	v_rcp_f32_e32 v40, v40
	v_rcp_f32_e32 v41, v41
	v_rcp_f32_e32 v42, v42
	v_mul_f32_e32 v35, v35, v43
	v_mul_f32_e32 v36, v36, v44
	v_mul_f32_e32 v37, v37, v45
	v_mul_f32_e32 v38, v38, v46
	v_mul_f32_e32 v39, v39, v47
	v_mul_f32_e32 v40, v32, v40
	v_mul_f32_e32 v41, v33, v41
	v_mul_f32_e32 v42, v34, v42
	v_cvt_pk_bf16_f32 v32, v36, v37
	v_cvt_pk_bf16_f32 v33, v38, v39
	v_cvt_pk_bf16_f32 v34, v40, v41
	v_cvt_pk_bf16_f32 v35, v42, v35
; __device__ __forceinline__ unsigned cvt_pk_bf16(float lo, float hi) { unsigned r; asm volatile("v_cvt_pk_bf16_f32 %0, %1, %2" : "=v"(r) : "v"(lo), "v"(hi)); return r; }
;     __device__ __forceinline__ static float sg(float g, float u) { return g * u * __builtin_amdgcn_rcpf(1.0f + __builtin_amdgcn_exp2f(-1.4426950408889634f * g)); }
;     __device__ __forceinline__ void operator()(const f32x4 (&acc)[2][2][4][2], const Unit& u, int wr, int wc, int fr, int fq) const {
;     ...
;             for (int m = 0; m < 4; ++m) { const int row = row0 + ai * HALF + m * 16;
;                 const float rstd = __builtin_amdgcn_rsqf(SS[row] * (1.0f / 1024.0f) + 1e-6f);
;                 const f32x4 g0 = acc[ai][0][m][0] * rstd + bv[0][0], g1 = acc[ai][0][m][1] * rstd + bv[0][1], u0 = acc[ai][1][m][0] * rstd + bv[1][0], u1 = acc[ai][1][m][1] * rstd + bv[1][1];
;                 u32x4 w; w.x = cvt_pk_bf16(sg(g0[0], u0[0]), sg(g0[1], u0[1])); w.y = cvt_pk_bf16(sg(g0[2], u0[2]), sg(g0[3], u0[3]));
;                 w.z = cvt_pk_bf16(sg(g1[0], u1[0]), sg(g1[1], u1[1])); w.w = cvt_pk_bf16(sg(g1[2], u1[2]), sg(g1[3], u1[3]));
;                 *(u32x4*)(O + (size_t)row * ldc + j0) = w; }
	global_store_dwordx4 v[50:51], v[32:35], off
	s_nop 0
	s_nop 0
	v_add_u32_e32 v33, 0xa0, v160
	v_mad_i64_i32 v[34:35], s[0:1], v33, s67, v[164:165]
	v_lshl_add_u64 v[34:35], v[34:35], 0, v[166:167]
	v_fmamk_f32 v32, v187, 0x3a800000, v172
	v_rsq_f32_e32 v32, v32
	s_nop 0
	v_pk_fma_f32 v[26:27], v[26:27], v[32:33], v[138:139] op_sel_hi:[1,0,1]
	v_pk_fma_f32 v[18:19], v[18:19], v[32:33], v[130:131] op_sel_hi:[1,0,1]
	v_pk_fma_f32 v[30:31], v[30:31], v[32:33], v[142:143] op_sel_hi:[1,0,1]
	v_pk_fma_f32 v[28:29], v[28:29], v[32:33], v[140:141] op_sel_hi:[1,0,1]
	v_pk_fma_f32 v[24:25], v[24:25], v[32:33], v[136:137] op_sel_hi:[1,0,1]
	v_pk_fma_f32 v[22:23], v[22:23], v[32:33], v[134:135] op_sel_hi:[1,0,1]
	v_pk_fma_f32 v[20:21], v[20:21], v[32:33], v[132:133] op_sel_hi:[1,0,1]
	v_pk_fma_f32 v[16:17], v[16:17], v[32:33], v[128:129] op_sel_hi:[1,0,1]
	v_mul_f32_e32 v19, v27, v19
	v_mul_f32_e32 v27, 0xbfb8aa3b, v27
	v_mul_f32_e32 v20, v28, v20
	v_mul_f32_e32 v28, 0xbfb8aa3b, v28
	v_mul_f32_e32 v21, v29, v21
	v_mul_f32_e32 v29, 0xbfb8aa3b, v29
	v_mul_f32_e32 v22, v30, v22
	v_mul_f32_e32 v30, 0xbfb8aa3b, v30
	v_mul_f32_e32 v23, v31, v23
	v_mul_f32_e32 v31, 0xbfb8aa3b, v31
	v_mul_f32_e32 v16, v24, v16
	v_mul_f32_e32 v24, 0xbfb8aa3b, v24
	v_mul_f32_e32 v17, v25, v17
	v_mul_f32_e32 v25, 0xbfb8aa3b, v25
	v_mul_f32_e32 v18, v26, v18
	v_mul_f32_e32 v26, 0xbfb8aa3b, v26
	v_exp_f32_e32 v27, v27
	v_exp_f32_e32 v28, v28
	v_exp_f32_e32 v29, v29
	v_exp_f32_e32 v30, v30
	v_exp_f32_e32 v31, v31
	v_exp_f32_e32 v24, v24
	v_exp_f32_e32 v25, v25
	v_exp_f32_e32 v26, v26
	v_add_f32_e32 v27, 1.0, v27
	v_add_f32_e32 v28, 1.0, v28
	v_add_f32_e32 v29, 1.0, v29
	v_add_f32_e32 v30, 1.0, v30
	v_add_f32_e32 v31, 1.0, v31
	v_add_f32_e32 v24, 1.0, v24
	v_add_f32_e32 v25, 1.0, v25
	v_add_f32_e32 v26, 1.0, v26
	v_rcp_f32_e32 v27, v27
	v_rcp_f32_e32 v28, v28
	v_rcp_f32_e32 v29, v29
	v_rcp_f32_e32 v30, v30
	v_rcp_f32_e32 v31, v31
	v_rcp_f32_e32 v24, v24
	v_rcp_f32_e32 v25, v25
	v_rcp_f32_e32 v26, v26
	v_mul_f32_e32 v19, v19, v27
	v_mul_f32_e32 v20, v20, v28
	v_mul_f32_e32 v21, v21, v29
	v_mul_f32_e32 v22, v22, v30
	v_mul_f32_e32 v23, v23, v31
	v_mul_f32_e32 v24, v16, v24
	v_mul_f32_e32 v25, v17, v25
	v_mul_f32_e32 v26, v18, v26
	v_cvt_pk_bf16_f32 v16, v20, v21
	v_cvt_pk_bf16_f32 v17, v22, v23
	v_cvt_pk_bf16_f32 v18, v24, v25
	v_cvt_pk_bf16_f32 v19, v26, v19
	global_store_dwordx4 v[34:35], v[16:19], off
	s_nop 0
	s_nop 0
	v_add_u32_e32 v17, 0xb0, v160
	v_mad_i64_i32 v[18:19], s[0:1], v17, s67, v[164:165]
	v_lshl_add_u64 v[18:19], v[18:19], 0, v[166:167]
	v_fmamk_f32 v16, v188, 0x3a800000, v172
	v_rsq_f32_e32 v16, v16
	s_nop 0
	v_pk_fma_f32 v[10:11], v[10:11], v[16:17], v[138:139] op_sel_hi:[1,0,1]
	v_pk_fma_f32 v[2:3], v[2:3], v[16:17], v[130:131] op_sel_hi:[1,0,1]
	v_pk_fma_f32 v[14:15], v[14:15], v[16:17], v[142:143] op_sel_hi:[1,0,1]
	v_pk_fma_f32 v[12:13], v[12:13], v[16:17], v[140:141] op_sel_hi:[1,0,1]
	v_pk_fma_f32 v[8:9], v[8:9], v[16:17], v[136:137] op_sel_hi:[1,0,1]
	v_pk_fma_f32 v[6:7], v[6:7], v[16:17], v[134:135] op_sel_hi:[1,0,1]
	v_pk_fma_f32 v[4:5], v[4:5], v[16:17], v[132:133] op_sel_hi:[1,0,1]
	v_pk_fma_f32 v[0:1], v[0:1], v[16:17], v[128:129] op_sel_hi:[1,0,1]
	v_mul_f32_e32 v3, v11, v3
	v_mul_f32_e32 v11, 0xbfb8aa3b, v11
	v_mul_f32_e32 v4, v12, v4
	v_mul_f32_e32 v12, 0xbfb8aa3b, v12
	v_mul_f32_e32 v5, v13, v5
	v_mul_f32_e32 v13, 0xbfb8aa3b, v13
	v_mul_f32_e32 v6, v14, v6
	v_mul_f32_e32 v14, 0xbfb8aa3b, v14
	v_mul_f32_e32 v7, v15, v7
	v_mul_f32_e32 v15, 0xbfb8aa3b, v15
	v_mul_f32_e32 v0, v8, v0
	v_mul_f32_e32 v8, 0xbfb8aa3b, v8
	v_mul_f32_e32 v1, v9, v1
	v_mul_f32_e32 v9, 0xbfb8aa3b, v9
	v_mul_f32_e32 v2, v10, v2
	v_mul_f32_e32 v10, 0xbfb8aa3b, v10
	v_exp_f32_e32 v11, v11
	v_exp_f32_e32 v12, v12
	v_exp_f32_e32 v13, v13
	v_exp_f32_e32 v14, v14
	v_exp_f32_e32 v15, v15
	v_exp_f32_e32 v8, v8
	v_exp_f32_e32 v9, v9
	v_exp_f32_e32 v10, v10
	v_add_f32_e32 v11, 1.0, v11
	v_add_f32_e32 v12, 1.0, v12
	v_add_f32_e32 v13, 1.0, v13
	v_add_f32_e32 v14, 1.0, v14
	v_add_f32_e32 v15, 1.0, v15
	v_add_f32_e32 v8, 1.0, v8
	v_add_f32_e32 v9, 1.0, v9
	v_add_f32_e32 v10, 1.0, v10
	v_rcp_f32_e32 v11, v11
	v_rcp_f32_e32 v12, v12
	v_rcp_f32_e32 v13, v13
	v_rcp_f32_e32 v14, v14
	v_rcp_f32_e32 v15, v15
	v_rcp_f32_e32 v8, v8
	v_rcp_f32_e32 v9, v9
	v_rcp_f32_e32 v10, v10
	v_mul_f32_e32 v3, v3, v11
	v_mul_f32_e32 v4, v4, v12
	v_mul_f32_e32 v5, v5, v13
	v_mul_f32_e32 v6, v6, v14
	v_mul_f32_e32 v7, v7, v15
	v_mul_f32_e32 v8, v0, v8
	v_mul_f32_e32 v9, v1, v9
	v_mul_f32_e32 v10, v2, v10
	v_cvt_pk_bf16_f32 v0, v4, v5
	v_cvt_pk_bf16_f32 v1, v6, v7
	v_cvt_pk_bf16_f32 v2, v8, v9
	v_cvt_pk_bf16_f32 v3, v10, v3
	global_store_dwordx4 v[18:19], v[0:3], off
	s_cbranch_vccnz .LBB0_792
	s_andn2_b64 vcc, exec, s[40:41]
	s_cbranch_vccnz .LBB0_791
	s_barrier
	s_branch .LBB0_791

; __device__ __forceinline__ unsigned cvt_pk_bf16(float lo, float hi) { unsigned r; asm volatile("v_cvt_pk_bf16_f32 %0, %1, %2" : "=v"(r) : "v"(lo), "v"(hi)); return r; }
;     __device__ __forceinline__ static float sg(float g, float u) { return g * u * __builtin_amdgcn_rcpf(1.0f + __builtin_amdgcn_exp2f(-1.4426950408889634f * g)); }
;     __device__ __forceinline__ void operator()(const f32x4 (&acc)[2][2][4][2], const Unit& u, int wr, int wc, int fr, int fq) const {
;         const int row0 = u.pm * BM + wr * 64 + fr, col0 = u.pn * BM + wc * 32 + 8 * fq, j0 = u.pn * HALF + wc * 32 + 8 * fq;
;         const float* bp = bt + (size_t)((u.pm * BM) >> 12) * (2 * 2816) + col0;
;         f32x4 bv[2][2];
; #pragma unroll
;         for (int bj = 0; bj < 2; ++bj)
; #pragma unroll
;             for (int n = 0; n < 2; ++n) bv[bj][n] = *(const f32x4*)(bp + bj * HALF + 4 * n);
; #pragma unroll
;         for (int ai = 0; ai < 2; ++ai)
; #pragma unroll
;             for (int m = 0; m < 4; ++m) { const int row = row0 + ai * HALF + m * 16;
;                 const float rstd = __builtin_amdgcn_rsqf(SS[row] * (1.0f / 1024.0f) + 1e-6f);
;                 const f32x4 g0 = acc[ai][0][m][0] * rstd + bv[0][0], g1 = acc[ai][0][m][1] * rstd + bv[0][1], u0 = acc[ai][1][m][0] * rstd + bv[1][0], u1 = acc[ai][1][m][1] * rstd + bv[1][1];
;                 u32x4 w; w.x = cvt_pk_bf16(sg(g0[0], u0[0]), sg(g0[1], u0[1])); w.y = cvt_pk_bf16(sg(g0[2], u0[2]), sg(g0[3], u0[3]));
;                 w.z = cvt_pk_bf16(sg(g1[0], u1[0]), sg(g1[1], u1[1])); w.w = cvt_pk_bf16(sg(g1[2], u1[2]), sg(g1[3], u1[3]));
;                 *(u32x4*)(O + (size_t)row * ldc + j0) = w; }
.LBB0_1312:
	s_lshl_b32 s0, s68, 8
	v_mov_b32_e32 v129, v204
	s_add_i32 s0, s0, s58
	s_lshl_b32 s1, s69, 8
	v_lshrrev_b32_e32 v128, 1, v129
	v_and_or_b32 v160, v129, 15, s0
	s_or_b32 s1, s1, s59
	v_and_b32_e32 v166, 24, v128
	v_ashrrev_i32_e32 v161, 31, v160
	v_or_b32_e32 v128, s1, v166
	s_lshl_b32 s1, s69, 7
	v_lshl_add_u64 v[162:163], v[160:161], 2, s[10:11]
	s_or_b32 s22, s1, s59
	s_ashr_i32 s1, s68, 4
	global_load_dword v161, v[162:163], off
	global_load_dword v182, v[162:163], off offset:64
	global_load_dword v183, v[162:163], off offset:128
	global_load_dword v184, v[162:163], off offset:192
	global_load_dword v185, v[162:163], off offset:512
	global_load_dword v186, v[162:163], off offset:576
	global_load_dword v187, v[162:163], off offset:640
	global_load_dword v188, v[162:163], off offset:704
	s_mul_hi_i32 s23, s1, 0x5800
	s_mulk_i32 s1, 0x5800
	s_add_u32 s0, s53, s1
	s_addc_u32 s1, s54, s23
	v_ashrrev_i32_e32 v129, 31, v128
	v_lshl_add_u64 v[128:129], v[128:129], 2, s[0:1]
	global_load_dwordx4 v[140:143], v[128:129], off
	global_load_dwordx4 v[136:139], v[128:129], off offset:16
	global_load_dwordx4 v[132:135], v[128:129], off offset:512
	s_nop 0
	global_load_dwordx4 v[128:131], v[128:129], off offset:528
	v_or_b32_e32 v166, s22, v166
	v_mov_b64_e32 v[164:165], s[20:21]
	v_ashrrev_i32_e32 v167, 31, v166
	v_mad_i64_i32 v[174:175], s[0:1], v160, s65, v[164:165]
	v_or_b32_e32 v176, 16, v160
	v_lshlrev_b64 v[166:167], 1, v[166:167]
	v_ashrrev_i32_e32 v177, 31, v176
	v_lshl_add_u64 v[174:175], v[174:175], 0, v[166:167]
	v_lshl_add_u64 v[180:181], v[176:177], 2, s[10:11]
	s_and_b64 vcc, exec, s[6:7]
	s_mov_b64 s[6:7], -1
	s_waitcnt vmcnt(0)
	v_fmamk_f32 v161, v161, 0x3a800000, v172
	v_rsq_f32_e32 v178, v161
	s_nop 0
	v_pk_fma_f32 v[126:127], v[126:127], v[178:179], v[138:139] op_sel_hi:[1,0,1]
	v_pk_fma_f32 v[122:123], v[122:123], v[178:179], v[142:143] op_sel_hi:[1,0,1]
	v_pk_fma_f32 v[114:115], v[114:115], v[178:179], v[130:131] op_sel_hi:[1,0,1]
	v_pk_fma_f32 v[120:121], v[120:121], v[178:179], v[140:141] op_sel_hi:[1,0,1]
	v_pk_fma_f32 v[124:125], v[124:125], v[178:179], v[136:137] op_sel_hi:[1,0,1]
	v_pk_fma_f32 v[118:119], v[118:119], v[178:179], v[134:135] op_sel_hi:[1,0,1]
	v_pk_fma_f32 v[116:117], v[116:117], v[178:179], v[132:133] op_sel_hi:[1,0,1]
	v_pk_fma_f32 v[112:113], v[112:113], v[178:179], v[128:129] op_sel_hi:[1,0,1]
	v_mul_f32_e32 v115, v127, v115
	v_mul_f32_e32 v127, 0xbfb8aa3b, v127
	v_mul_f32_e32 v116, v120, v116
	v_mul_f32_e32 v120, 0xbfb8aa3b, v120
	v_mul_f32_e32 v117, v121, v117
	v_mul_f32_e32 v121, 0xbfb8aa3b, v121
	v_mul_f32_e32 v118, v122, v118
	v_mul_f32_e32 v122, 0xbfb8aa3b, v122
	v_mul_f32_e32 v119, v123, v119
	v_mul_f32_e32 v123, 0xbfb8aa3b, v123
	v_mul_f32_e32 v112, v124, v112
	v_mul_f32_e32 v124, 0xbfb8aa3b, v124
	v_mul_f32_e32 v113, v125, v113
	v_mul_f32_e32 v125, 0xbfb8aa3b, v125
	v_mul_f32_e32 v114, v126, v114
	v_mul_f32_e32 v126, 0xbfb8aa3b, v126
	v_exp_f32_e32 v127, v127
	v_exp_f32_e32 v120, v120
	v_exp_f32_e32 v121, v121
	v_exp_f32_e32 v122, v122
	v_exp_f32_e32 v123, v123
	v_exp_f32_e32 v124, v124
	v_exp_f32_e32 v125, v125
	v_exp_f32_e32 v126, v126
	v_add_f32_e32 v127, 1.0, v127
	v_add_f32_e32 v120, 1.0, v120
	v_add_f32_e32 v121, 1.0, v121
	v_add_f32_e32 v122, 1.0, v122
	v_add_f32_e32 v123, 1.0, v123
	v_add_f32_e32 v124, 1.0, v124
	v_add_f32_e32 v125, 1.0, v125
	v_add_f32_e32 v126, 1.0, v126
	v_rcp_f32_e32 v127, v127
	v_rcp_f32_e32 v120, v120
	v_rcp_f32_e32 v121, v121
	v_rcp_f32_e32 v122, v122
	v_rcp_f32_e32 v123, v123
	v_rcp_f32_e32 v124, v124
	v_rcp_f32_e32 v125, v125
	v_rcp_f32_e32 v126, v126
	v_mul_f32_e32 v115, v115, v127
	v_mul_f32_e32 v116, v116, v120
	v_mul_f32_e32 v117, v117, v121
	v_mul_f32_e32 v118, v118, v122
	v_mul_f32_e32 v119, v119, v123
	v_mul_f32_e32 v120, v112, v124
	v_mul_f32_e32 v121, v113, v125
	v_mul_f32_e32 v122, v114, v126
	v_cvt_pk_bf16_f32 v112, v116, v117
	v_cvt_pk_bf16_f32 v113, v118, v119
	v_cvt_pk_bf16_f32 v114, v120, v121
	v_cvt_pk_bf16_f32 v115, v122, v115
	global_store_dwordx4 v[174:175], v[112:115], off
	s_nop 0
	s_nop 0
	v_or_b32_e32 v112, 32, v160
	v_mad_i64_i32 v[114:115], s[0:1], v176, s65, v[164:165]
	v_lshl_add_u64 v[114:115], v[114:115], 0, v[166:167]
	v_fmamk_f32 v113, v182, 0x3a800000, v172
	v_rsq_f32_e32 v116, v113
	v_ashrrev_i32_e32 v113, 31, v112
	v_lshl_add_u64 v[118:119], v[112:113], 2, s[10:11]
	v_pk_fma_f32 v[106:107], v[106:107], v[116:117], v[138:139] op_sel_hi:[1,0,1]
	v_pk_fma_f32 v[98:99], v[98:99], v[116:117], v[130:131] op_sel_hi:[1,0,1]
	v_pk_fma_f32 v[110:111], v[110:111], v[116:117], v[142:143] op_sel_hi:[1,0,1]
	v_pk_fma_f32 v[108:109], v[108:109], v[116:117], v[140:141] op_sel_hi:[1,0,1]
	v_pk_fma_f32 v[104:105], v[104:105], v[116:117], v[136:137] op_sel_hi:[1,0,1]
	v_pk_fma_f32 v[102:103], v[102:103], v[116:117], v[134:135] op_sel_hi:[1,0,1]
	v_pk_fma_f32 v[100:101], v[100:101], v[116:117], v[132:133] op_sel_hi:[1,0,1]
	v_pk_fma_f32 v[96:97], v[96:97], v[116:117], v[128:129] op_sel_hi:[1,0,1]
	v_mul_f32_e32 v99, v107, v99
	v_mul_f32_e32 v107, 0xbfb8aa3b, v107
	v_mul_f32_e32 v100, v108, v100
	v_mul_f32_e32 v108, 0xbfb8aa3b, v108
	v_mul_f32_e32 v101, v109, v101
	v_mul_f32_e32 v109, 0xbfb8aa3b, v109
	v_mul_f32_e32 v102, v110, v102
	v_mul_f32_e32 v110, 0xbfb8aa3b, v110
	v_mul_f32_e32 v103, v111, v103
	v_mul_f32_e32 v111, 0xbfb8aa3b, v111
	v_mul_f32_e32 v96, v104, v96
	v_mul_f32_e32 v104, 0xbfb8aa3b, v104
	v_mul_f32_e32 v97, v105, v97
	v_mul_f32_e32 v105, 0xbfb8aa3b, v105
	v_mul_f32_e32 v98, v106, v98
	v_mul_f32_e32 v106, 0xbfb8aa3b, v106
	v_exp_f32_e32 v107, v107
	v_exp_f32_e32 v108, v108
	v_exp_f32_e32 v109, v109
	v_exp_f32_e32 v110, v110
; __device__ __forceinline__ unsigned cvt_pk_bf16(float lo, float hi) { unsigned r; asm volatile("v_cvt_pk_bf16_f32 %0, %1, %2" : "=v"(r) : "v"(lo), "v"(hi)); return r; }
;     __device__ __forceinline__ static float sg(float g, float u) { return g * u * __builtin_amdgcn_rcpf(1.0f + __builtin_amdgcn_exp2f(-1.4426950408889634f * g)); }
;     __device__ __forceinline__ void operator()(const f32x4 (&acc)[2][2][4][2], const Unit& u, int wr, int wc, int fr, int fq) const {
;     ...
;             for (int m = 0; m < 4; ++m) { const int row = row0 + ai * HALF + m * 16;
;                 const float rstd = __builtin_amdgcn_rsqf(SS[row] * (1.0f / 1024.0f) + 1e-6f);
;                 const f32x4 g0 = acc[ai][0][m][0] * rstd + bv[0][0], g1 = acc[ai][0][m][1] * rstd + bv[0][1], u0 = acc[ai][1][m][0] * rstd + bv[1][0], u1 = acc[ai][1][m][1] * rstd + bv[1][1];
;                 u32x4 w; w.x = cvt_pk_bf16(sg(g0[0], u0[0]), sg(g0[1], u0[1])); w.y = cvt_pk_bf16(sg(g0[2], u0[2]), sg(g0[3], u0[3]));
;                 w.z = cvt_pk_bf16(sg(g1[0], u1[0]), sg(g1[1], u1[1])); w.w = cvt_pk_bf16(sg(g1[2], u1[2]), sg(g1[3], u1[3]));
;                 *(u32x4*)(O + (size_t)row * ldc + j0) = w; }
	v_exp_f32_e32 v111, v111
	v_exp_f32_e32 v104, v104
	v_exp_f32_e32 v105, v105
	v_exp_f32_e32 v106, v106
	v_add_f32_e32 v107, 1.0, v107
	v_add_f32_e32 v108, 1.0, v108
	v_add_f32_e32 v109, 1.0, v109
	v_add_f32_e32 v110, 1.0, v110
	v_add_f32_e32 v111, 1.0, v111
	v_add_f32_e32 v104, 1.0, v104
	v_add_f32_e32 v105, 1.0, v105
	v_add_f32_e32 v106, 1.0, v106
	v_rcp_f32_e32 v107, v107
	v_rcp_f32_e32 v108, v108
	v_rcp_f32_e32 v109, v109
	v_rcp_f32_e32 v110, v110
	v_rcp_f32_e32 v111, v111
	v_rcp_f32_e32 v104, v104
	v_rcp_f32_e32 v105, v105
	v_rcp_f32_e32 v106, v106
	v_mul_f32_e32 v99, v99, v107
	v_mul_f32_e32 v100, v100, v108
	v_mul_f32_e32 v101, v101, v109
	v_mul_f32_e32 v102, v102, v110
	v_mul_f32_e32 v103, v103, v111
	v_mul_f32_e32 v104, v96, v104
	v_mul_f32_e32 v105, v97, v105
	v_mul_f32_e32 v106, v98, v106
	v_cvt_pk_bf16_f32 v96, v100, v101
	v_cvt_pk_bf16_f32 v97, v102, v103
	v_cvt_pk_bf16_f32 v98, v104, v105
	v_cvt_pk_bf16_f32 v99, v106, v99
	global_store_dwordx4 v[114:115], v[96:99], off
	s_nop 0
	s_nop 0
	v_or_b32_e32 v96, 48, v160
	v_mad_i64_i32 v[98:99], s[0:1], v112, s65, v[164:165]
	v_lshl_add_u64 v[98:99], v[98:99], 0, v[166:167]
	v_fmamk_f32 v97, v183, 0x3a800000, v172
	v_rsq_f32_e32 v100, v97
	v_ashrrev_i32_e32 v97, 31, v96
	v_lshl_add_u64 v[102:103], v[96:97], 2, s[10:11]
	v_pk_fma_f32 v[90:91], v[90:91], v[100:101], v[138:139] op_sel_hi:[1,0,1]
	v_pk_fma_f32 v[82:83], v[82:83], v[100:101], v[130:131] op_sel_hi:[1,0,1]
	v_pk_fma_f32 v[94:95], v[94:95], v[100:101], v[142:143] op_sel_hi:[1,0,1]
	v_pk_fma_f32 v[92:93], v[92:93], v[100:101], v[140:141] op_sel_hi:[1,0,1]
	v_pk_fma_f32 v[88:89], v[88:89], v[100:101], v[136:137] op_sel_hi:[1,0,1]
	v_pk_fma_f32 v[86:87], v[86:87], v[100:101], v[134:135] op_sel_hi:[1,0,1]
	v_pk_fma_f32 v[84:85], v[84:85], v[100:101], v[132:133] op_sel_hi:[1,0,1]
	v_pk_fma_f32 v[80:81], v[80:81], v[100:101], v[128:129] op_sel_hi:[1,0,1]
	v_mul_f32_e32 v83, v91, v83
	v_mul_f32_e32 v91, 0xbfb8aa3b, v91
	v_mul_f32_e32 v84, v92, v84
	v_mul_f32_e32 v92, 0xbfb8aa3b, v92
	v_mul_f32_e32 v85, v93, v85
	v_mul_f32_e32 v93, 0xbfb8aa3b, v93
	v_mul_f32_e32 v86, v94, v86
	v_mul_f32_e32 v94, 0xbfb8aa3b, v94
	v_mul_f32_e32 v87, v95, v87
	v_mul_f32_e32 v95, 0xbfb8aa3b, v95
	v_mul_f32_e32 v80, v88, v80
	v_mul_f32_e32 v88, 0xbfb8aa3b, v88
	v_mul_f32_e32 v81, v89, v81
	v_mul_f32_e32 v89, 0xbfb8aa3b, v89
	v_mul_f32_e32 v82, v90, v82
	v_mul_f32_e32 v90, 0xbfb8aa3b, v90
	v_exp_f32_e32 v91, v91
	v_exp_f32_e32 v92, v92
	v_exp_f32_e32 v93, v93
	v_exp_f32_e32 v94, v94
	v_exp_f32_e32 v95, v95
	v_exp_f32_e32 v88, v88
	v_exp_f32_e32 v89, v89
	v_exp_f32_e32 v90, v90
	v_add_f32_e32 v91, 1.0, v91
	v_add_f32_e32 v92, 1.0, v92
	v_add_f32_e32 v93, 1.0, v93
	v_add_f32_e32 v94, 1.0, v94
	v_add_f32_e32 v95, 1.0, v95
	v_add_f32_e32 v88, 1.0, v88
	v_add_f32_e32 v89, 1.0, v89
	v_add_f32_e32 v90, 1.0, v90
	v_rcp_f32_e32 v91, v91
	v_rcp_f32_e32 v92, v92
	v_rcp_f32_e32 v93, v93
	v_rcp_f32_e32 v94, v94
	v_rcp_f32_e32 v95, v95
	v_rcp_f32_e32 v88, v88
	v_rcp_f32_e32 v89, v89
	v_rcp_f32_e32 v90, v90
	v_mul_f32_e32 v83, v83, v91
	v_mul_f32_e32 v84, v84, v92
	v_mul_f32_e32 v85, v85, v93
	v_mul_f32_e32 v86, v86, v94
	v_mul_f32_e32 v87, v87, v95
	v_mul_f32_e32 v88, v80, v88
	v_mul_f32_e32 v89, v81, v89
	v_mul_f32_e32 v90, v82, v90
	v_cvt_pk_bf16_f32 v80, v84, v85
	v_cvt_pk_bf16_f32 v81, v86, v87
	v_cvt_pk_bf16_f32 v82, v88, v89
	v_cvt_pk_bf16_f32 v83, v90, v83
	global_store_dwordx4 v[98:99], v[80:83], off
	s_nop 0
	s_nop 0
	v_mad_i64_i32 v[82:83], s[0:1], v96, s65, v[164:165]
	v_lshl_add_u64 v[82:83], v[82:83], 0, v[166:167]
	v_fmamk_f32 v80, v184, 0x3a800000, v172
	v_rsq_f32_e32 v80, v80
	s_nop 0
	v_pk_fma_f32 v[74:75], v[74:75], v[80:81], v[138:139] op_sel_hi:[1,0,1]
	v_pk_fma_f32 v[66:67], v[66:67], v[80:81], v[130:131] op_sel_hi:[1,0,1]
	v_pk_fma_f32 v[78:79], v[78:79], v[80:81], v[142:143] op_sel_hi:[1,0,1]
	v_pk_fma_f32 v[76:77], v[76:77], v[80:81], v[140:141] op_sel_hi:[1,0,1]
	v_pk_fma_f32 v[72:73], v[72:73], v[80:81], v[136:137] op_sel_hi:[1,0,1]
	v_pk_fma_f32 v[70:71], v[70:71], v[80:81], v[134:135] op_sel_hi:[1,0,1]
	v_pk_fma_f32 v[68:69], v[68:69], v[80:81], v[132:133] op_sel_hi:[1,0,1]
	v_pk_fma_f32 v[64:65], v[64:65], v[80:81], v[128:129] op_sel_hi:[1,0,1]
	v_mul_f32_e32 v67, v75, v67
	v_mul_f32_e32 v75, 0xbfb8aa3b, v75
	v_mul_f32_e32 v68, v76, v68
	v_mul_f32_e32 v76, 0xbfb8aa3b, v76
	v_mul_f32_e32 v69, v77, v69
	v_mul_f32_e32 v77, 0xbfb8aa3b, v77
	v_mul_f32_e32 v70, v78, v70
	v_mul_f32_e32 v78, 0xbfb8aa3b, v78
	v_mul_f32_e32 v71, v79, v71
	v_mul_f32_e32 v79, 0xbfb8aa3b, v79
	v_mul_f32_e32 v64, v72, v64
	v_mul_f32_e32 v72, 0xbfb8aa3b, v72
	v_mul_f32_e32 v65, v73, v65
	v_mul_f32_e32 v73, 0xbfb8aa3b, v73
	v_mul_f32_e32 v66, v74, v66
	v_mul_f32_e32 v74, 0xbfb8aa3b, v74
	v_exp_f32_e32 v75, v75
	v_exp_f32_e32 v76, v76
	v_exp_f32_e32 v77, v77
	v_exp_f32_e32 v78, v78
	v_exp_f32_e32 v79, v79
	v_exp_f32_e32 v72, v72
	v_exp_f32_e32 v73, v73
	v_exp_f32_e32 v74, v74
	v_add_f32_e32 v75, 1.0, v75
	v_add_f32_e32 v76, 1.0, v76
	v_add_f32_e32 v77, 1.0, v77
	v_add_f32_e32 v78, 1.0, v78
	v_add_f32_e32 v79, 1.0, v79
	v_add_f32_e32 v72, 1.0, v72
	v_add_f32_e32 v73, 1.0, v73
	v_add_f32_e32 v74, 1.0, v74
	v_rcp_f32_e32 v75, v75
	v_rcp_f32_e32 v76, v76
	v_rcp_f32_e32 v77, v77
	v_rcp_f32_e32 v78, v78
	v_rcp_f32_e32 v79, v79
	v_rcp_f32_e32 v72, v72
	v_rcp_f32_e32 v73, v73
	v_rcp_f32_e32 v74, v74
	v_mul_f32_e32 v67, v67, v75
	v_mul_f32_e32 v68, v68, v76
	v_mul_f32_e32 v69, v69, v77
	v_mul_f32_e32 v70, v70, v78
	v_mul_f32_e32 v71, v71, v79
	v_mul_f32_e32 v72, v64, v72
	v_mul_f32_e32 v73, v65, v73
	v_mul_f32_e32 v74, v66, v74
	v_cvt_pk_bf16_f32 v64, v68, v69
; __device__ __forceinline__ unsigned cvt_pk_bf16(float lo, float hi) { unsigned r; asm volatile("v_cvt_pk_bf16_f32 %0, %1, %2" : "=v"(r) : "v"(lo), "v"(hi)); return r; }
;     __device__ __forceinline__ static float sg(float g, float u) { return g * u * __builtin_amdgcn_rcpf(1.0f + __builtin_amdgcn_exp2f(-1.4426950408889634f * g)); }
;     __device__ __forceinline__ void operator()(const f32x4 (&acc)[2][2][4][2], const Unit& u, int wr, int wc, int fr, int fq) const {
;     ...
;             for (int m = 0; m < 4; ++m) { const int row = row0 + ai * HALF + m * 16;
;                 const float rstd = __builtin_amdgcn_rsqf(SS[row] * (1.0f / 1024.0f) + 1e-6f);
;                 const f32x4 g0 = acc[ai][0][m][0] * rstd + bv[0][0], g1 = acc[ai][0][m][1] * rstd + bv[0][1], u0 = acc[ai][1][m][0] * rstd + bv[1][0], u1 = acc[ai][1][m][1] * rstd + bv[1][1];
;                 u32x4 w; w.x = cvt_pk_bf16(sg(g0[0], u0[0]), sg(g0[1], u0[1])); w.y = cvt_pk_bf16(sg(g0[2], u0[2]), sg(g0[3], u0[3]));
;                 w.z = cvt_pk_bf16(sg(g1[0], u1[0]), sg(g1[1], u1[1])); w.w = cvt_pk_bf16(sg(g1[2], u1[2]), sg(g1[3], u1[3]));
;                 *(u32x4*)(O + (size_t)row * ldc + j0) = w; }
	v_cvt_pk_bf16_f32 v65, v70, v71
	v_cvt_pk_bf16_f32 v66, v72, v73
	v_cvt_pk_bf16_f32 v67, v74, v67
	global_store_dwordx4 v[82:83], v[64:67], off
	s_nop 0
	s_nop 0
	v_add_u32_e32 v65, 0x80, v160
	v_mad_i64_i32 v[66:67], s[0:1], v65, s65, v[164:165]
	v_lshl_add_u64 v[66:67], v[66:67], 0, v[166:167]
	v_fmamk_f32 v64, v185, 0x3a800000, v172
	v_rsq_f32_e32 v64, v64
	s_nop 0
	v_pk_fma_f32 v[58:59], v[58:59], v[64:65], v[138:139] op_sel_hi:[1,0,1]
	v_pk_fma_f32 v[50:51], v[50:51], v[64:65], v[130:131] op_sel_hi:[1,0,1]
	v_pk_fma_f32 v[62:63], v[62:63], v[64:65], v[142:143] op_sel_hi:[1,0,1]
	v_pk_fma_f32 v[60:61], v[60:61], v[64:65], v[140:141] op_sel_hi:[1,0,1]
	v_pk_fma_f32 v[56:57], v[56:57], v[64:65], v[136:137] op_sel_hi:[1,0,1]
	v_pk_fma_f32 v[54:55], v[54:55], v[64:65], v[134:135] op_sel_hi:[1,0,1]
	v_pk_fma_f32 v[52:53], v[52:53], v[64:65], v[132:133] op_sel_hi:[1,0,1]
	v_pk_fma_f32 v[48:49], v[48:49], v[64:65], v[128:129] op_sel_hi:[1,0,1]
	v_mul_f32_e32 v51, v59, v51
	v_mul_f32_e32 v59, 0xbfb8aa3b, v59
	v_mul_f32_e32 v52, v60, v52
	v_mul_f32_e32 v60, 0xbfb8aa3b, v60
	v_mul_f32_e32 v53, v61, v53
	v_mul_f32_e32 v61, 0xbfb8aa3b, v61
	v_mul_f32_e32 v54, v62, v54
	v_mul_f32_e32 v62, 0xbfb8aa3b, v62
	v_mul_f32_e32 v55, v63, v55
	v_mul_f32_e32 v63, 0xbfb8aa3b, v63
	v_mul_f32_e32 v48, v56, v48
	v_mul_f32_e32 v56, 0xbfb8aa3b, v56
	v_mul_f32_e32 v49, v57, v49
	v_mul_f32_e32 v57, 0xbfb8aa3b, v57
	v_mul_f32_e32 v50, v58, v50
	v_mul_f32_e32 v58, 0xbfb8aa3b, v58
	v_exp_f32_e32 v59, v59
	v_exp_f32_e32 v60, v60
	v_exp_f32_e32 v61, v61
	v_exp_f32_e32 v62, v62
	v_exp_f32_e32 v63, v63
	v_exp_f32_e32 v56, v56
	v_exp_f32_e32 v57, v57
	v_exp_f32_e32 v58, v58
	v_add_f32_e32 v59, 1.0, v59
	v_add_f32_e32 v60, 1.0, v60
	v_add_f32_e32 v61, 1.0, v61
	v_add_f32_e32 v62, 1.0, v62
	v_add_f32_e32 v63, 1.0, v63
	v_add_f32_e32 v56, 1.0, v56
	v_add_f32_e32 v57, 1.0, v57
	v_add_f32_e32 v58, 1.0, v58
	v_rcp_f32_e32 v59, v59
	v_rcp_f32_e32 v60, v60
	v_rcp_f32_e32 v61, v61
	v_rcp_f32_e32 v62, v62
	v_rcp_f32_e32 v63, v63
	v_rcp_f32_e32 v56, v56
	v_rcp_f32_e32 v57, v57
	v_rcp_f32_e32 v58, v58
	v_mul_f32_e32 v51, v51, v59
	v_mul_f32_e32 v52, v52, v60
	v_mul_f32_e32 v53, v53, v61
	v_mul_f32_e32 v54, v54, v62
	v_mul_f32_e32 v55, v55, v63
	v_mul_f32_e32 v56, v48, v56
	v_mul_f32_e32 v57, v49, v57
	v_mul_f32_e32 v58, v50, v58
	v_cvt_pk_bf16_f32 v48, v52, v53
	v_cvt_pk_bf16_f32 v49, v54, v55
	v_cvt_pk_bf16_f32 v50, v56, v57
	v_cvt_pk_bf16_f32 v51, v58, v51
	global_store_dwordx4 v[66:67], v[48:51], off
	s_nop 0
	s_nop 0
	v_add_u32_e32 v49, 0x90, v160
	v_mad_i64_i32 v[50:51], s[0:1], v49, s65, v[164:165]
	v_lshl_add_u64 v[50:51], v[50:51], 0, v[166:167]
	v_fmamk_f32 v48, v186, 0x3a800000, v172
	v_rsq_f32_e32 v48, v48
	s_nop 0
	v_pk_fma_f32 v[42:43], v[42:43], v[48:49], v[138:139] op_sel_hi:[1,0,1]
	v_pk_fma_f32 v[34:35], v[34:35], v[48:49], v[130:131] op_sel_hi:[1,0,1]
	v_pk_fma_f32 v[46:47], v[46:47], v[48:49], v[142:143] op_sel_hi:[1,0,1]
	v_pk_fma_f32 v[44:45], v[44:45], v[48:49], v[140:141] op_sel_hi:[1,0,1]
	v_pk_fma_f32 v[40:41], v[40:41], v[48:49], v[136:137] op_sel_hi:[1,0,1]
	v_pk_fma_f32 v[38:39], v[38:39], v[48:49], v[134:135] op_sel_hi:[1,0,1]
	v_pk_fma_f32 v[36:37], v[36:37], v[48:49], v[132:133] op_sel_hi:[1,0,1]
	v_pk_fma_f32 v[32:33], v[32:33], v[48:49], v[128:129] op_sel_hi:[1,0,1]
	v_mul_f32_e32 v35, v43, v35
	v_mul_f32_e32 v43, 0xbfb8aa3b, v43
	v_mul_f32_e32 v36, v44, v36
	v_mul_f32_e32 v44, 0xbfb8aa3b, v44
	v_mul_f32_e32 v37, v45, v37
	v_mul_f32_e32 v45, 0xbfb8aa3b, v45
	v_mul_f32_e32 v38, v46, v38
	v_mul_f32_e32 v46, 0xbfb8aa3b, v46
	v_mul_f32_e32 v39, v47, v39
	v_mul_f32_e32 v47, 0xbfb8aa3b, v47
	v_mul_f32_e32 v32, v40, v32
	v_mul_f32_e32 v40, 0xbfb8aa3b, v40
	v_mul_f32_e32 v33, v41, v33
	v_mul_f32_e32 v41, 0xbfb8aa3b, v41
	v_mul_f32_e32 v34, v42, v34
	v_mul_f32_e32 v42, 0xbfb8aa3b, v42
	v_exp_f32_e32 v43, v43
	v_exp_f32_e32 v44, v44
	v_exp_f32_e32 v45, v45
	v_exp_f32_e32 v46, v46
	v_exp_f32_e32 v47, v47
	v_exp_f32_e32 v40, v40
	v_exp_f32_e32 v41, v41
	v_exp_f32_e32 v42, v42
	v_add_f32_e32 v43, 1.0, v43
	v_add_f32_e32 v44, 1.0, v44
	v_add_f32_e32 v45, 1.0, v45
	v_add_f32_e32 v46, 1.0, v46
	v_add_f32_e32 v47, 1.0, v47
	v_add_f32_e32 v40, 1.0, v40
	v_add_f32_e32 v41, 1.0, v41
	v_add_f32_e32 v42, 1.0, v42
	v_rcp_f32_e32 v43, v43
	v_rcp_f32_e32 v44, v44
	v_rcp_f32_e32 v45, v45
	v_rcp_f32_e32 v46, v46
	v_rcp_f32_e32 v47, v47
	v_rcp_f32_e32 v40, v40
	v_rcp_f32_e32 v41, v41
	v_rcp_f32_e32 v42, v42
	v_mul_f32_e32 v35, v35, v43
	v_mul_f32_e32 v36, v36, v44
	v_mul_f32_e32 v37, v37, v45
	v_mul_f32_e32 v38, v38, v46
	v_mul_f32_e32 v39, v39, v47
	v_mul_f32_e32 v40, v32, v40
	v_mul_f32_e32 v41, v33, v41
	v_mul_f32_e32 v42, v34, v42
	v_cvt_pk_bf16_f32 v32, v36, v37
	v_cvt_pk_bf16_f32 v33, v38, v39
	v_cvt_pk_bf16_f32 v34, v40, v41
	v_cvt_pk_bf16_f32 v35, v42, v35
; __device__ __forceinline__ unsigned cvt_pk_bf16(float lo, float hi) { unsigned r; asm volatile("v_cvt_pk_bf16_f32 %0, %1, %2" : "=v"(r) : "v"(lo), "v"(hi)); return r; }
;     __device__ __forceinline__ static float sg(float g, float u) { return g * u * __builtin_amdgcn_rcpf(1.0f + __builtin_amdgcn_exp2f(-1.4426950408889634f * g)); }
;     __device__ __forceinline__ void operator()(const f32x4 (&acc)[2][2][4][2], const Unit& u, int wr, int wc, int fr, int fq) const {
;     ...
;             for (int m = 0; m < 4; ++m) { const int row = row0 + ai * HALF + m * 16;
;                 const float rstd = __builtin_amdgcn_rsqf(SS[row] * (1.0f / 1024.0f) + 1e-6f);
;                 const f32x4 g0 = acc[ai][0][m][0] * rstd + bv[0][0], g1 = acc[ai][0][m][1] * rstd + bv[0][1], u0 = acc[ai][1][m][0] * rstd + bv[1][0], u1 = acc[ai][1][m][1] * rstd + bv[1][1];
;                 u32x4 w; w.x = cvt_pk_bf16(sg(g0[0], u0[0]), sg(g0[1], u0[1])); w.y = cvt_pk_bf16(sg(g0[2], u0[2]), sg(g0[3], u0[3]));
;                 w.z = cvt_pk_bf16(sg(g1[0], u1[0]), sg(g1[1], u1[1])); w.w = cvt_pk_bf16(sg(g1[2], u1[2]), sg(g1[3], u1[3]));
;                 *(u32x4*)(O + (size_t)row * ldc + j0) = w; }
	global_store_dwordx4 v[50:51], v[32:35], off
	s_nop 0
	s_nop 0
	v_add_u32_e32 v33, 0xa0, v160
	v_mad_i64_i32 v[34:35], s[0:1], v33, s65, v[164:165]
	v_lshl_add_u64 v[34:35], v[34:35], 0, v[166:167]
	v_fmamk_f32 v32, v187, 0x3a800000, v172
	v_rsq_f32_e32 v32, v32
	s_nop 0
	v_pk_fma_f32 v[26:27], v[26:27], v[32:33], v[138:139] op_sel_hi:[1,0,1]
	v_pk_fma_f32 v[18:19], v[18:19], v[32:33], v[130:131] op_sel_hi:[1,0,1]
	v_pk_fma_f32 v[30:31], v[30:31], v[32:33], v[142:143] op_sel_hi:[1,0,1]
	v_pk_fma_f32 v[28:29], v[28:29], v[32:33], v[140:141] op_sel_hi:[1,0,1]
	v_pk_fma_f32 v[24:25], v[24:25], v[32:33], v[136:137] op_sel_hi:[1,0,1]
	v_pk_fma_f32 v[22:23], v[22:23], v[32:33], v[134:135] op_sel_hi:[1,0,1]
	v_pk_fma_f32 v[20:21], v[20:21], v[32:33], v[132:133] op_sel_hi:[1,0,1]
	v_pk_fma_f32 v[16:17], v[16:17], v[32:33], v[128:129] op_sel_hi:[1,0,1]
	v_mul_f32_e32 v19, v27, v19
	v_mul_f32_e32 v27, 0xbfb8aa3b, v27
	v_mul_f32_e32 v20, v28, v20
	v_mul_f32_e32 v28, 0xbfb8aa3b, v28
	v_mul_f32_e32 v21, v29, v21
	v_mul_f32_e32 v29, 0xbfb8aa3b, v29
	v_mul_f32_e32 v22, v30, v22
	v_mul_f32_e32 v30, 0xbfb8aa3b, v30
	v_mul_f32_e32 v23, v31, v23
	v_mul_f32_e32 v31, 0xbfb8aa3b, v31
	v_mul_f32_e32 v16, v24, v16
	v_mul_f32_e32 v24, 0xbfb8aa3b, v24
	v_mul_f32_e32 v17, v25, v17
	v_mul_f32_e32 v25, 0xbfb8aa3b, v25
	v_mul_f32_e32 v18, v26, v18
	v_mul_f32_e32 v26, 0xbfb8aa3b, v26
	v_exp_f32_e32 v27, v27
	v_exp_f32_e32 v28, v28
	v_exp_f32_e32 v29, v29
	v_exp_f32_e32 v30, v30
	v_exp_f32_e32 v31, v31
	v_exp_f32_e32 v24, v24
	v_exp_f32_e32 v25, v25
	v_exp_f32_e32 v26, v26
	v_add_f32_e32 v27, 1.0, v27
	v_add_f32_e32 v28, 1.0, v28
	v_add_f32_e32 v29, 1.0, v29
	v_add_f32_e32 v30, 1.0, v30
	v_add_f32_e32 v31, 1.0, v31
	v_add_f32_e32 v24, 1.0, v24
	v_add_f32_e32 v25, 1.0, v25
	v_add_f32_e32 v26, 1.0, v26
	v_rcp_f32_e32 v27, v27
	v_rcp_f32_e32 v28, v28
	v_rcp_f32_e32 v29, v29
	v_rcp_f32_e32 v30, v30
	v_rcp_f32_e32 v31, v31
	v_rcp_f32_e32 v24, v24
	v_rcp_f32_e32 v25, v25
	v_rcp_f32_e32 v26, v26
	v_mul_f32_e32 v19, v19, v27
	v_mul_f32_e32 v20, v20, v28
	v_mul_f32_e32 v21, v21, v29
	v_mul_f32_e32 v22, v22, v30
	v_mul_f32_e32 v23, v23, v31
	v_mul_f32_e32 v24, v16, v24
	v_mul_f32_e32 v25, v17, v25
	v_mul_f32_e32 v26, v18, v26
	v_cvt_pk_bf16_f32 v16, v20, v21
	v_cvt_pk_bf16_f32 v17, v22, v23
	v_cvt_pk_bf16_f32 v18, v24, v25
	v_cvt_pk_bf16_f32 v19, v26, v19
	global_store_dwordx4 v[34:35], v[16:19], off
	s_nop 0
	s_nop 0
	v_add_u32_e32 v17, 0xb0, v160
	v_mad_i64_i32 v[18:19], s[0:1], v17, s65, v[164:165]
	v_lshl_add_u64 v[18:19], v[18:19], 0, v[166:167]
	v_fmamk_f32 v16, v188, 0x3a800000, v172
	v_rsq_f32_e32 v16, v16
	s_nop 0
	v_pk_fma_f32 v[10:11], v[10:11], v[16:17], v[138:139] op_sel_hi:[1,0,1]
	v_pk_fma_f32 v[2:3], v[2:3], v[16:17], v[130:131] op_sel_hi:[1,0,1]
	v_pk_fma_f32 v[14:15], v[14:15], v[16:17], v[142:143] op_sel_hi:[1,0,1]
	v_pk_fma_f32 v[12:13], v[12:13], v[16:17], v[140:141] op_sel_hi:[1,0,1]
	v_pk_fma_f32 v[8:9], v[8:9], v[16:17], v[136:137] op_sel_hi:[1,0,1]
	v_pk_fma_f32 v[6:7], v[6:7], v[16:17], v[134:135] op_sel_hi:[1,0,1]
	v_pk_fma_f32 v[4:5], v[4:5], v[16:17], v[132:133] op_sel_hi:[1,0,1]
	v_pk_fma_f32 v[0:1], v[0:1], v[16:17], v[128:129] op_sel_hi:[1,0,1]
	v_mul_f32_e32 v3, v11, v3
	v_mul_f32_e32 v11, 0xbfb8aa3b, v11
	v_mul_f32_e32 v4, v12, v4
	v_mul_f32_e32 v12, 0xbfb8aa3b, v12
	v_mul_f32_e32 v5, v13, v5
	v_mul_f32_e32 v13, 0xbfb8aa3b, v13
	v_mul_f32_e32 v6, v14, v6
	v_mul_f32_e32 v14, 0xbfb8aa3b, v14
	v_mul_f32_e32 v7, v15, v7
	v_mul_f32_e32 v15, 0xbfb8aa3b, v15
	v_mul_f32_e32 v0, v8, v0
	v_mul_f32_e32 v8, 0xbfb8aa3b, v8
	v_mul_f32_e32 v1, v9, v1
	v_mul_f32_e32 v9, 0xbfb8aa3b, v9
	v_mul_f32_e32 v2, v10, v2
	v_mul_f32_e32 v10, 0xbfb8aa3b, v10
	v_exp_f32_e32 v11, v11
	v_exp_f32_e32 v12, v12
	v_exp_f32_e32 v13, v13
	v_exp_f32_e32 v14, v14
	v_exp_f32_e32 v15, v15
	v_exp_f32_e32 v8, v8
	v_exp_f32_e32 v9, v9
	v_exp_f32_e32 v10, v10
	v_add_f32_e32 v11, 1.0, v11
	v_add_f32_e32 v12, 1.0, v12
	v_add_f32_e32 v13, 1.0, v13
	v_add_f32_e32 v14, 1.0, v14
	v_add_f32_e32 v15, 1.0, v15
	v_add_f32_e32 v8, 1.0, v8
	v_add_f32_e32 v9, 1.0, v9
	v_add_f32_e32 v10, 1.0, v10
	v_rcp_f32_e32 v11, v11
	v_rcp_f32_e32 v12, v12
	v_rcp_f32_e32 v13, v13
	v_rcp_f32_e32 v14, v14
	v_rcp_f32_e32 v15, v15
	v_rcp_f32_e32 v8, v8
	v_rcp_f32_e32 v9, v9
	v_rcp_f32_e32 v10, v10
	v_mul_f32_e32 v3, v3, v11
	v_mul_f32_e32 v4, v4, v12
	v_mul_f32_e32 v5, v5, v13
	v_mul_f32_e32 v6, v6, v14
	v_mul_f32_e32 v7, v7, v15
	v_mul_f32_e32 v8, v0, v8
	v_mul_f32_e32 v9, v1, v9
	v_mul_f32_e32 v10, v2, v10
	v_cvt_pk_bf16_f32 v0, v4, v5
	v_cvt_pk_bf16_f32 v1, v6, v7
	v_cvt_pk_bf16_f32 v2, v8, v9
	v_cvt_pk_bf16_f32 v3, v10, v3
	global_store_dwordx4 v[18:19], v[0:3], off
	s_cbranch_vccnz .LBB0_1300
	s_andn2_b64 vcc, exec, s[26:27]
	s_cbranch_vccnz .LBB0_1299
	s_barrier
	s_branch .LBB0_1299
